# lru_post: store-drain waits at unit start removed, per-row counted waits
# baseline (speedup 1.0000x reference)
.LBB0_1093:
	s_cmpk_lt_i32 s10, 0x900
	s_mov_b64 s[0:1], -1
	s_cbranch_scc0 .LBB0_1103
	s_cmpk_gt_i32 s10, 0x3ff
	s_cbranch_scc0 .LBB0_1097
	s_cmpk_gt_u32 s10, 0x7ff
	s_cbranch_scc0 .LBB0_1097
	s_add_i32 s0, s10, 0xfffff800
	s_and_b32 s96, s0, 0xffffffc0
	s_and_b32 s2, s10, 63
	s_lshl_b64 s[0:1], s[96:97], 11
	v_readlane_b32 s11, v252, 46
	s_add_u32 s11, s11, s0
	v_readlane_b32 s0, v252, 47
	v_mov_b32_e32 v4, v232
	s_addc_u32 s12, s0, s1
	s_add_i32 s0, s8, 0xfffe0000
	v_ashrrev_i32_e32 v0, 3, v4
	s_and_b32 s0, s0, 0x7ffff000
	s_lshl_b32 s1, s2, 6
	v_and_b32_e32 v0, -8, v0
	s_or_b32 s96, s1, s0
	v_ashrrev_i32_e32 v1, 31, v0
	v_lshl_add_u64 v[0:1], s[96:97], 0, v[0:1]
	v_mov_b64_e32 v[2:3], s[82:83]
	s_movk_i32 s13, 0x3800
	v_mad_u64_u32 v[8:9], s[0:1], v0, s13, v[2:3]
	v_lshlrev_b32_e32 v0, 3, v4
	v_and_b32_e32 v10, 0x1f8, v0
	v_mad_i32_i24 v9, v1, s13, v9
	v_lshlrev_b32_e32 v16, 1, v10
	s_lshl_b32 s0, s2, 11
	v_lshl_add_u64 v[12:13], v[8:9], 0, v[16:17]
	s_add_u32 s0, s11, s0
	v_add_co_u32_e32 v14, vcc, s57, v12
	s_addc_u32 s1, s12, 0
	v_lshlrev_b32_e32 v4, 2, v10
	v_addc_co_u32_e32 v15, vcc, 0, v13, vcc
	global_load_dwordx4 v[0:3], v4, s[0:1] offset:16
	s_nop 0
	global_load_dwordx4 v[4:7], v4, s[0:1]
	s_mov_b64 s[0:1], 0x3800
	v_mov_b64_e32 v[24:25], v[12:13]
	v_add_co_u32_e32 v14, vcc, 0x3000, v12
	s_nop 1
	v_addc_co_u32_e32 v15, vcc, 0, v13, vcc
	global_load_dwordx4 v[32:35], v[12:13], off offset:3072
	global_load_dwordx4 v[64:67], v[14:15], off offset:1024
	v_lshl_add_u64 v[12:13], v[12:13], 0, s[0:1]
	v_lshl_add_u64 v[14:15], v[14:15], 0, s[0:1]
	global_load_dwordx4 v[36:39], v[12:13], off offset:3072
	global_load_dwordx4 v[68:71], v[14:15], off offset:1024
	v_lshl_add_u64 v[12:13], v[12:13], 0, s[0:1]
	v_lshl_add_u64 v[14:15], v[14:15], 0, s[0:1]
	global_load_dwordx4 v[40:43], v[12:13], off offset:3072
	global_load_dwordx4 v[72:75], v[14:15], off offset:1024
	v_lshl_add_u64 v[12:13], v[12:13], 0, s[0:1]
	v_lshl_add_u64 v[14:15], v[14:15], 0, s[0:1]
	global_load_dwordx4 v[44:47], v[12:13], off offset:3072
	global_load_dwordx4 v[76:79], v[14:15], off offset:1024
	v_lshl_add_u64 v[12:13], v[12:13], 0, s[0:1]
	v_lshl_add_u64 v[14:15], v[14:15], 0, s[0:1]
	global_load_dwordx4 v[48:51], v[12:13], off offset:3072
	global_load_dwordx4 v[80:83], v[14:15], off offset:1024
	v_lshl_add_u64 v[12:13], v[12:13], 0, s[0:1]
	v_lshl_add_u64 v[14:15], v[14:15], 0, s[0:1]
	global_load_dwordx4 v[52:55], v[12:13], off offset:3072
	global_load_dwordx4 v[84:87], v[14:15], off offset:1024
	v_lshl_add_u64 v[12:13], v[12:13], 0, s[0:1]
	v_lshl_add_u64 v[14:15], v[14:15], 0, s[0:1]
	global_load_dwordx4 v[56:59], v[12:13], off offset:3072
	global_load_dwordx4 v[88:91], v[14:15], off offset:1024
	v_lshl_add_u64 v[12:13], v[12:13], 0, s[0:1]
	v_lshl_add_u64 v[14:15], v[14:15], 0, s[0:1]
	global_load_dwordx4 v[60:63], v[12:13], off offset:3072
	global_load_dwordx4 v[92:95], v[14:15], off offset:1024
	s_waitcnt vmcnt(14)
	v_lshlrev_b32_e32 v18, 16, v32
	v_and_b32_e32 v19, 0xffff0000, v32
	v_lshlrev_b32_e32 v22, 16, v64
	v_and_b32_e32 v23, 0xffff0000, v64
	v_pk_fma_f32 v[18:19], v[4:5], v[22:23], v[18:19]
	v_cvt_pk_bf16_f32 v32, v18, v19
	v_lshlrev_b32_e32 v18, 16, v33
	v_and_b32_e32 v19, 0xffff0000, v33
	v_lshlrev_b32_e32 v22, 16, v65
	v_and_b32_e32 v23, 0xffff0000, v65
	v_pk_fma_f32 v[18:19], v[6:7], v[22:23], v[18:19]
	v_cvt_pk_bf16_f32 v33, v18, v19
	v_lshlrev_b32_e32 v18, 16, v34
	v_and_b32_e32 v19, 0xffff0000, v34
	v_lshlrev_b32_e32 v22, 16, v66
	v_and_b32_e32 v23, 0xffff0000, v66
	v_pk_fma_f32 v[18:19], v[0:1], v[22:23], v[18:19]
	v_cvt_pk_bf16_f32 v34, v18, v19
	v_lshlrev_b32_e32 v18, 16, v35
	v_and_b32_e32 v19, 0xffff0000, v35
	v_lshlrev_b32_e32 v22, 16, v67
	v_and_b32_e32 v23, 0xffff0000, v67
	v_pk_fma_f32 v[18:19], v[2:3], v[22:23], v[18:19]
	v_cvt_pk_bf16_f32 v35, v18, v19
	global_store_dwordx4 v[24:25], v[32:35], off offset:3072
	s_waitcnt vmcnt(13)
	v_lshl_add_u64 v[24:25], v[24:25], 0, s[0:1]
	v_lshlrev_b32_e32 v18, 16, v36
	v_and_b32_e32 v19, 0xffff0000, v36
	v_lshlrev_b32_e32 v22, 16, v68
	v_and_b32_e32 v23, 0xffff0000, v68
	v_pk_fma_f32 v[18:19], v[4:5], v[22:23], v[18:19]
	v_cvt_pk_bf16_f32 v36, v18, v19
	v_lshlrev_b32_e32 v18, 16, v37
	v_and_b32_e32 v19, 0xffff0000, v37
	v_lshlrev_b32_e32 v22, 16, v69
	v_and_b32_e32 v23, 0xffff0000, v69
	v_pk_fma_f32 v[18:19], v[6:7], v[22:23], v[18:19]
	v_cvt_pk_bf16_f32 v37, v18, v19
	v_lshlrev_b32_e32 v18, 16, v38
	v_and_b32_e32 v19, 0xffff0000, v38
	v_lshlrev_b32_e32 v22, 16, v70
	v_and_b32_e32 v23, 0xffff0000, v70
	v_pk_fma_f32 v[18:19], v[0:1], v[22:23], v[18:19]
	v_cvt_pk_bf16_f32 v38, v18, v19
	v_lshlrev_b32_e32 v18, 16, v39
	v_and_b32_e32 v19, 0xffff0000, v39
	v_lshlrev_b32_e32 v22, 16, v71
	v_and_b32_e32 v23, 0xffff0000, v71
	v_pk_fma_f32 v[18:19], v[2:3], v[22:23], v[18:19]
	v_cvt_pk_bf16_f32 v39, v18, v19
	global_store_dwordx4 v[24:25], v[36:39], off offset:3072
	s_waitcnt vmcnt(12)
	v_lshl_add_u64 v[24:25], v[24:25], 0, s[0:1]
	v_lshlrev_b32_e32 v18, 16, v40
	v_and_b32_e32 v19, 0xffff0000, v40
	v_lshlrev_b32_e32 v22, 16, v72
	v_and_b32_e32 v23, 0xffff0000, v72
	v_pk_fma_f32 v[18:19], v[4:5], v[22:23], v[18:19]
	v_cvt_pk_bf16_f32 v40, v18, v19
	v_lshlrev_b32_e32 v18, 16, v41
	v_and_b32_e32 v19, 0xffff0000, v41
	v_lshlrev_b32_e32 v22, 16, v73
	v_and_b32_e32 v23, 0xffff0000, v73
	v_pk_fma_f32 v[18:19], v[6:7], v[22:23], v[18:19]
	v_cvt_pk_bf16_f32 v41, v18, v19
	v_lshlrev_b32_e32 v18, 16, v42
	v_and_b32_e32 v19, 0xffff0000, v42
	v_lshlrev_b32_e32 v22, 16, v74
	v_and_b32_e32 v23, 0xffff0000, v74
	v_pk_fma_f32 v[18:19], v[0:1], v[22:23], v[18:19]
	v_cvt_pk_bf16_f32 v42, v18, v19
	v_lshlrev_b32_e32 v18, 16, v43
	v_and_b32_e32 v19, 0xffff0000, v43
	v_lshlrev_b32_e32 v22, 16, v75
	v_and_b32_e32 v23, 0xffff0000, v75
	v_pk_fma_f32 v[18:19], v[2:3], v[22:23], v[18:19]
	v_cvt_pk_bf16_f32 v43, v18, v19
	global_store_dwordx4 v[24:25], v[40:43], off offset:3072
	s_waitcnt vmcnt(11)
	v_lshl_add_u64 v[24:25], v[24:25], 0, s[0:1]
	v_lshlrev_b32_e32 v18, 16, v44
	v_and_b32_e32 v19, 0xffff0000, v44
	v_lshlrev_b32_e32 v22, 16, v76
	v_and_b32_e32 v23, 0xffff0000, v76
	v_pk_fma_f32 v[18:19], v[4:5], v[22:23], v[18:19]
	v_cvt_pk_bf16_f32 v44, v18, v19
	v_lshlrev_b32_e32 v18, 16, v45
	v_and_b32_e32 v19, 0xffff0000, v45
	v_lshlrev_b32_e32 v22, 16, v77
	v_and_b32_e32 v23, 0xffff0000, v77
	v_pk_fma_f32 v[18:19], v[6:7], v[22:23], v[18:19]
	v_cvt_pk_bf16_f32 v45, v18, v19
	v_lshlrev_b32_e32 v18, 16, v46
	v_and_b32_e32 v19, 0xffff0000, v46
	v_lshlrev_b32_e32 v22, 16, v78
	v_and_b32_e32 v23, 0xffff0000, v78
	v_pk_fma_f32 v[18:19], v[0:1], v[22:23], v[18:19]
	v_cvt_pk_bf16_f32 v46, v18, v19
	v_lshlrev_b32_e32 v18, 16, v47
	v_and_b32_e32 v19, 0xffff0000, v47
	v_lshlrev_b32_e32 v22, 16, v79
	v_and_b32_e32 v23, 0xffff0000, v79
	v_pk_fma_f32 v[18:19], v[2:3], v[22:23], v[18:19]
	v_cvt_pk_bf16_f32 v47, v18, v19
	global_store_dwordx4 v[24:25], v[44:47], off offset:3072
	s_waitcnt vmcnt(10)
	v_lshl_add_u64 v[24:25], v[24:25], 0, s[0:1]
	v_lshlrev_b32_e32 v18, 16, v48
	v_and_b32_e32 v19, 0xffff0000, v48
	v_lshlrev_b32_e32 v22, 16, v80
	v_and_b32_e32 v23, 0xffff0000, v80
	v_pk_fma_f32 v[18:19], v[4:5], v[22:23], v[18:19]
	v_cvt_pk_bf16_f32 v48, v18, v19
	v_lshlrev_b32_e32 v18, 16, v49
	v_and_b32_e32 v19, 0xffff0000, v49
	v_lshlrev_b32_e32 v22, 16, v81
	v_and_b32_e32 v23, 0xffff0000, v81
	v_pk_fma_f32 v[18:19], v[6:7], v[22:23], v[18:19]
	v_cvt_pk_bf16_f32 v49, v18, v19
	v_lshlrev_b32_e32 v18, 16, v50
	v_and_b32_e32 v19, 0xffff0000, v50
	v_lshlrev_b32_e32 v22, 16, v82
	v_and_b32_e32 v23, 0xffff0000, v82
	v_pk_fma_f32 v[18:19], v[0:1], v[22:23], v[18:19]
	v_cvt_pk_bf16_f32 v50, v18, v19
	v_lshlrev_b32_e32 v18, 16, v51
	v_and_b32_e32 v19, 0xffff0000, v51
	v_lshlrev_b32_e32 v22, 16, v83
	v_and_b32_e32 v23, 0xffff0000, v83
	v_pk_fma_f32 v[18:19], v[2:3], v[22:23], v[18:19]
	v_cvt_pk_bf16_f32 v51, v18, v19
	global_store_dwordx4 v[24:25], v[48:51], off offset:3072
	s_waitcnt vmcnt(9)
	v_lshl_add_u64 v[24:25], v[24:25], 0, s[0:1]
	v_lshlrev_b32_e32 v18, 16, v52
	v_and_b32_e32 v19, 0xffff0000, v52
	v_lshlrev_b32_e32 v22, 16, v84
	v_and_b32_e32 v23, 0xffff0000, v84
	v_pk_fma_f32 v[18:19], v[4:5], v[22:23], v[18:19]
	v_cvt_pk_bf16_f32 v52, v18, v19
	v_lshlrev_b32_e32 v18, 16, v53
	v_and_b32_e32 v19, 0xffff0000, v53
	v_lshlrev_b32_e32 v22, 16, v85
	v_and_b32_e32 v23, 0xffff0000, v85
	v_pk_fma_f32 v[18:19], v[6:7], v[22:23], v[18:19]
	v_cvt_pk_bf16_f32 v53, v18, v19
	v_lshlrev_b32_e32 v18, 16, v54
	v_and_b32_e32 v19, 0xffff0000, v54
	v_lshlrev_b32_e32 v22, 16, v86
	v_and_b32_e32 v23, 0xffff0000, v86
	v_pk_fma_f32 v[18:19], v[0:1], v[22:23], v[18:19]
	v_cvt_pk_bf16_f32 v54, v18, v19
	v_lshlrev_b32_e32 v18, 16, v55
	v_and_b32_e32 v19, 0xffff0000, v55
	v_lshlrev_b32_e32 v22, 16, v87
	v_and_b32_e32 v23, 0xffff0000, v87
	v_pk_fma_f32 v[18:19], v[2:3], v[22:23], v[18:19]
	v_cvt_pk_bf16_f32 v55, v18, v19
	global_store_dwordx4 v[24:25], v[52:55], off offset:3072
	s_waitcnt vmcnt(8)
	v_lshl_add_u64 v[24:25], v[24:25], 0, s[0:1]
	v_lshlrev_b32_e32 v18, 16, v56
	v_and_b32_e32 v19, 0xffff0000, v56
	v_lshlrev_b32_e32 v22, 16, v88
	v_and_b32_e32 v23, 0xffff0000, v88
	v_pk_fma_f32 v[18:19], v[4:5], v[22:23], v[18:19]
	v_cvt_pk_bf16_f32 v56, v18, v19
	v_lshlrev_b32_e32 v18, 16, v57
	v_and_b32_e32 v19, 0xffff0000, v57
	v_lshlrev_b32_e32 v22, 16, v89
	v_and_b32_e32 v23, 0xffff0000, v89
	v_pk_fma_f32 v[18:19], v[6:7], v[22:23], v[18:19]
	v_cvt_pk_bf16_f32 v57, v18, v19
	v_lshlrev_b32_e32 v18, 16, v58
	v_and_b32_e32 v19, 0xffff0000, v58
	v_lshlrev_b32_e32 v22, 16, v90
	v_and_b32_e32 v23, 0xffff0000, v90
	v_pk_fma_f32 v[18:19], v[0:1], v[22:23], v[18:19]
	v_cvt_pk_bf16_f32 v58, v18, v19
	v_lshlrev_b32_e32 v18, 16, v59
	v_and_b32_e32 v19, 0xffff0000, v59
	v_lshlrev_b32_e32 v22, 16, v91
	v_and_b32_e32 v23, 0xffff0000, v91
	v_pk_fma_f32 v[18:19], v[2:3], v[22:23], v[18:19]
	v_cvt_pk_bf16_f32 v59, v18, v19
	global_store_dwordx4 v[24:25], v[56:59], off offset:3072
	s_waitcnt vmcnt(7)
	v_lshl_add_u64 v[24:25], v[24:25], 0, s[0:1]
	v_lshlrev_b32_e32 v18, 16, v60
	v_and_b32_e32 v19, 0xffff0000, v60
	v_lshlrev_b32_e32 v22, 16, v92
	v_and_b32_e32 v23, 0xffff0000, v92
	v_pk_fma_f32 v[18:19], v[4:5], v[22:23], v[18:19]
	v_cvt_pk_bf16_f32 v60, v18, v19
	v_lshlrev_b32_e32 v18, 16, v61
	v_and_b32_e32 v19, 0xffff0000, v61
	v_lshlrev_b32_e32 v22, 16, v93
	v_and_b32_e32 v23, 0xffff0000, v93
	v_pk_fma_f32 v[18:19], v[6:7], v[22:23], v[18:19]
	v_cvt_pk_bf16_f32 v61, v18, v19
	v_lshlrev_b32_e32 v18, 16, v62
	v_and_b32_e32 v19, 0xffff0000, v62
	v_lshlrev_b32_e32 v22, 16, v94
	v_and_b32_e32 v23, 0xffff0000, v94
	v_pk_fma_f32 v[18:19], v[0:1], v[22:23], v[18:19]
	v_cvt_pk_bf16_f32 v62, v18, v19
	v_lshlrev_b32_e32 v18, 16, v63
	v_and_b32_e32 v19, 0xffff0000, v63
	v_lshlrev_b32_e32 v22, 16, v95
	v_and_b32_e32 v23, 0xffff0000, v95
	v_pk_fma_f32 v[18:19], v[2:3], v[22:23], v[18:19]
	v_cvt_pk_bf16_f32 v63, v18, v19
	global_store_dwordx4 v[24:25], v[60:63], off offset:3072
	s_mov_b64 s[0:1], 0
